# rowpass mode 0 (phase 0): keep next-row prefetch in flight (global loads, counted wait) on top of v42
# baseline (speedup 1.0000x reference)
; DI void rowpass(const Cx& a, int mode, int l, int tid, int gw, int NGW) {
;     ...
;     const int chunk = (ROWS + NGW - 1) / NGW; const int r0 = gw * chunk; const int r1 = (r0 + chunk < ROWS) ? r0 + chunk : ROWS;
;     if (r0 >= r1) return;
;     const bool lastl = (l == DEPTH - 1);
;     const bool last = (mode == 2 && lastl);
;     const bool skipc = (mode != 0 && lastl);
;     const int l2 = (mode == 2) ? l + 1 : l; const int k2 = (mode == 1) ? 2 : 0;
;     f32x4 gnv[4], g2v[4], gtv[4], shv[4], scv[4];
; #pragma unroll
;     for (int j = 0; j < 4; ++j) { const int c = 4 * lane + 256 * j;
;         gnv[j] = (mode == 0) ? (f32x4){0.f, 0.f, 0.f, 0.f} : *(const f32x4*)(normg + ((size_t)l * 4 + (mode == 1 ? 1 : 3)) * DM + c);
;         g2v[j] = last ? (f32x4){0.f, 0.f, 0.f, 0.f} : *(const f32x4*)(normg + ((size_t)l2 * 4 + k2) * DM + c);
;         gtv[j] = (f32x4){0.f, 0.f, 0.f, 0.f}; shv[j] = gtv[j]; scv[j] = gtv[j]; }
;     int cur_mv = -1;
;     f32x4 xfc[4], xfn[4]; u32x2 xbc[4], xbn[4]; u32x2 yc[4], yn[4]; float sc_ = 0.f, sn_ = 0.f;
;     ...
;     RP_LOAD(r0, xfc, xbc, yc, sc_);
;     ...
;                 float s2 = 0.f;
; #pragma unroll
;                 for (int j = 0; j < 4; ++j) s2 += (v[j][0] * v[j][0] + v[j][1] * v[j][1]) + (v[j][2] * v[j][2] + v[j][3] * v[j][3]);
;                 const float rinv = rsqrtf(wave_sum(s2) * (1.f / DM) + EPS);
.LBB0_110:
	s_lshl_b32 s3, s3, 3
	s_abs_i32 s7, s3
	v_cvt_f32_u32_e32 v0, s7
	v_mov_b32_e32 v2, v196
	s_sub_i32 s9, 0, s7
	v_rcp_iflag_f32_e32 v0, v0
	v_ashrrev_i32_e32 v1, 6, v2
	v_lshl_add_u32 v1, s6, 3, v1
	s_add_i32 s8, s3, 0x10fff
	v_mul_f32_e32 v0, 0x4f7ffffe, v0
	v_cvt_u32_f32_e32 v0, v0
	s_xor_b32 s3, s8, s3
	s_abs_i32 s8, s8
	s_ashr_i32 s3, s3, 31
	v_readfirstlane_b32 s6, v0
	s_mul_i32 s9, s9, s6
	s_mul_hi_u32 s9, s6, s9
	s_add_i32 s6, s6, s9
	s_mul_hi_u32 s6, s8, s6
	s_mul_i32 s9, s6, s7
	s_sub_i32 s8, s8, s9
	s_add_i32 s9, s6, 1
	s_sub_i32 s10, s8, s7
	s_cmp_ge_u32 s8, s7
	s_cselect_b32 s6, s9, s6
	s_cselect_b32 s8, s10, s8
	s_add_i32 s9, s6, 1
	s_cmp_ge_u32 s8, s7
	s_cselect_b32 s6, s9, s6
	s_xor_b32 s6, s6, s3
	s_sub_i32 s3, s6, s3
	v_mul_lo_u32 v98, s3, v1
	v_add_u32_e32 v0, s3, v98
	v_min_i32_e32 v100, 0x11000, v0
	v_cmp_lt_i32_e32 vcc, v98, v100
	v_mbcnt_lo_u32_b32 v89, -1, 0
	s_and_saveexec_b64 s[6:7], vcc
	s_cbranch_execz .LBB0_117
	s_lshl_b32 s2, s2, 5
	s_ashr_i32 s3, s2, 31
	s_lshl_b64 s[2:3], s[2:3], 3
	s_add_u32 s2, s0, s2
	s_addc_u32 s3, s1, s3
	s_add_u32 s8, s2, 0x1000
	s_addc_u32 s9, s3, 0
	v_mov_b32_e32 v1, 0
	v_mov_b32_e32 v0, 0x1000
	global_load_dwordx2 v[4:5], v1, s[8:9] offset:48
	global_load_dwordx2 v[84:85], v0, s[2:3]
	global_load_dwordx2 v[86:87], v1, s[8:9] offset:16
	s_mov_b32 s18, 0x78787879
	v_mul_hi_i32 v3, v98, s18
	v_lshrrev_b32_e32 v6, 31, v3
	v_ashrrev_i32_e32 v3, 11, v3
	s_movk_i32 s19, 0xef00
	v_add_u32_e32 v20, v3, v6
	v_lshlrev_b32_e32 v0, 2, v2
	s_movk_i32 s20, 0x1000
	v_mad_i32_i24 v3, v20, s19, v98
	v_and_b32_e32 v88, 0xfc, v0
	v_add_u32_e32 v6, 0xfffff000, v3
	v_cmp_gt_i32_e32 vcc, s20, v3
	v_lshlrev_b32_e32 v0, 2, v88
	v_ashrrev_i32_e32 v21, 31, v20
	v_ashrrev_i32_e32 v7, 31, v3
	v_cndmask_b32_e32 v26, v6, v3, vcc
	v_cndmask_b32_e64 v3, 20, 24, vcc
	v_cndmask_b32_e32 v27, 0, v7, vcc
	v_lshlrev_b64 v[20:21], v3, v[20:21]
	s_add_u32 s10, s0, 0x100000
	v_ashrrev_i32_e32 v99, 31, v98
	s_addc_u32 s11, s1, 0
	v_lshlrev_b64 v[30:31], 11, v[98:99]
	s_add_u32 s21, s0, 0x2a00000
	s_addc_u32 s22, s1, 0
	v_or_b32_e32 v28, 0x300, v88
	v_lshlrev_b32_e32 v96, 2, v28
	s_mov_b64 s[8:9], 0x1000
	v_mov_b32_e32 v93, -1
	s_mov_b64 s[12:13], 0
	s_movk_i32 s23, 0xfff
	v_mov_b32_e32 v99, 0x358637bd
	s_mov_b32 s24, 0x800000
	s_mov_b64 s[14:15], 0x800
	v_mbcnt_hi_u32_b32 v101, -1, v89
	s_waitcnt vmcnt(2)
	v_lshl_add_u64 v[22:23], v[4:5], 0, v[0:1]
	flat_load_dwordx4 v[4:7], v[22:23]
	flat_load_dwordx4 v[8:11], v[22:23] offset:1024
	flat_load_dwordx4 v[12:15], v[22:23] offset:2048
	flat_load_dwordx4 v[16:19], v[22:23] offset:3072
	s_waitcnt vmcnt(0)
	v_cndmask_b32_e32 v25, v87, v85, vcc
	v_cndmask_b32_e32 v24, v86, v84, vcc
	v_lshlrev_b64 v[22:23], 12, v[26:27]
	v_lshl_add_u64 v[20:21], v[24:25], 0, v[20:21]
	v_lshl_add_u64 v[20:21], v[20:21], 0, v[22:23]
	v_lshl_add_u64 v[24:25], v[20:21], 0, v[0:1]
	flat_load_dwordx4 v[80:83], v[24:25]
	flat_load_dwordx4 v[60:63], v[24:25] offset:1024
	flat_load_dwordx4 v[32:35], v[24:25] offset:2048
	flat_load_dwordx4 v[20:23], v[24:25] offset:3072
	v_and_b32_e32 v0, 63, v2
	v_lshl_or_b32 v30, v0, 3, v30
	v_lshl_add_u64 v[2:3], s[0:1], 0, v[30:31]
	s_mov_b64 s[0:1], 0x3a00000
	v_or_b32_e32 v24, 0x100, v88
	v_or_b32_e32 v26, 0x200, v88
	v_lshl_add_u64 v[90:91], v[2:3], 0, s[0:1]
	v_mov_b32_e32 v2, v1
	v_mov_b32_e32 v3, v1
	v_mov_b32_e32 v0, v1
	v_lshlrev_b32_e32 v92, 2, v24
	v_lshlrev_b32_e32 v94, 2, v26
	v_mov_b64_e32 v[46:47], v[2:3]
	v_mov_b64_e32 v[38:39], v[2:3]
	v_mov_b64_e32 v[42:43], v[2:3]
	v_mov_b64_e32 v[26:27], v[2:3]
	v_mov_b64_e32 v[54:55], v[2:3]
	v_mov_b64_e32 v[58:59], v[2:3]
	v_mov_b64_e32 v[50:51], v[2:3]
	v_mov_b64_e32 v[30:31], v[2:3]
	v_mov_b64_e32 v[44:45], v[0:1]
	v_mov_b64_e32 v[36:37], v[0:1]
	v_mov_b64_e32 v[40:41], v[0:1]
	v_mov_b64_e32 v[24:25], v[0:1]
	v_mov_b64_e32 v[52:53], v[0:1]
	v_mov_b64_e32 v[56:57], v[0:1]
	v_mov_b64_e32 v[48:49], v[0:1]
	v_mov_b64_e32 v[28:29], v[0:1]
	s_waitcnt vmcnt(0) lgkmcnt(0)
	s_branch .LBB0_113
.LBB0_112:
	s_or_b64 exec, exec, s[16:17]
	v_pk_mul_f32 v[104:105], v[82:83], v[82:83]
	v_pk_mul_f32 v[106:107], v[80:81], v[80:81]
	v_mul_f32_e32 v0, v32, v32
	v_pk_mov_b32 v[108:109], v[106:107], v[104:105] op_sel:[1,0]
	v_mov_b32_e32 v107, v105
	v_pk_add_f32 v[104:105], v[108:109], v[106:107]
	v_pk_mul_f32 v[106:107], v[62:63], v[62:63]
	v_pk_mul_f32 v[108:109], v[60:61], v[60:61]
	v_pk_add_f32 v[104:105], v[104:105], v[104:105] op_sel_hi:[0,1]
	v_pk_mov_b32 v[110:111], v[108:109], v[106:107] op_sel:[1,0]
	v_mov_b32_e32 v109, v107
	v_pk_add_f32 v[106:107], v[110:111], v[108:109]
	v_pk_fma_f32 v[108:109], v[32:33], v[32:33], v[0:1] op_sel_hi:[1,1,0]
	v_mul_f32_e32 v0, v34, v34
	v_pk_add_f32 v[106:107], v[106:107], v[106:107] op_sel_hi:[0,1]
	v_pk_fma_f32 v[110:111], v[34:35], v[34:35], v[0:1] op_sel_hi:[1,1,0]
	v_mul_f32_e32 v108, v20, v20
	v_mul_f32_e32 v110, v21, v21
	v_mul_f32_e32 v106, v22, v22
	v_mul_f32_e32 v104, v23, v23
	v_pk_add_f32 v[108:109], v[108:109], v[110:111]
	v_pk_add_f32 v[104:105], v[106:107], v[104:105]
	v_and_b32_e32 v103, 64, v101
	v_pk_add_f32 v[104:105], v[108:109], v[104:105]
	s_and_b64 s[0:1], exec, s[2:3]
	v_add_f32_e32 v0, v104, v105
	v_add_u32_e32 v103, 64, v103
	v_xor_b32_e32 v104, 1, v101
	s_or_b64 s[12:13], s[0:1], s[12:13]
	v_cmp_lt_i32_e64 s[0:1], v104, v103
	v_mov_b32_e32 v105, s5
	v_mov_b32_e32 v106, s22
	v_cndmask_b32_e64 v104, v101, v104, s[0:1]
	v_lshlrev_b32_e32 v104, 2, v104
	ds_bpermute_b32 v104, v104, v0
	v_add_u32_e32 v95, 0xfffff000, v98
	v_cndmask_b32_e32 v105, v105, v106, vcc
	v_mov_b32_e32 v106, s4
	v_ashrrev_i32_e32 v97, 31, v98
	s_waitcnt lgkmcnt(0)
; DI unsigned pk2c(float lo, float hi) { unsigned r; asm("v_cvt_pk_bf16_f32 %0, %1, %2" : "=v"(r) : "v"(lo), "v"(hi)); return r; }
; DI void rowpass(const Cx& a, int mode, int l, int tid, int gw, int NGW) {
;     ...
;                 bf16_t* xp = RP_XDST(b, n);
; #pragma unroll
;                 for (int j = 0; j < 4; ++j) { u32x2 w; w.x = pk2c(v[j][0], v[j][1]); w.y = pk2c(v[j][2], v[j][3]); *(u32x2*)(xp + 4 * lane + 256 * j) = w; }
;                 float s2 = 0.f;
; #pragma unroll
;                 for (int j = 0; j < 4; ++j) s2 += (v[j][0] * v[j][0] + v[j][1] * v[j][1]) + (v[j][2] * v[j][2] + v[j][3] * v[j][3]);
;                 const float rinv = rsqrtf(wave_sum(s2) * (1.f / DM) + EPS);
; #pragma unroll
;                 for (int j = 0; j < 4; ++j) { const f32x4 h = v[j] * rinv * g2v[j] * (1.f + scv[j]) + shv[j]; u32x2 w; w.x = pk2c(h[0], h[1]); w.y = pk2c(h[2], h[3]);
;                     *(u32x2*)(H + (size_t)row * DM + 4 * lane + 256 * j) = w; }
;             }
;         }
; #pragma unroll
;         for (int j = 0; j < 4; ++j) { xfc[j] = xfn[j]; xbc[j] = xbn[j]; yc[j] = yn[j]; }
;         sc_ = sn_;
	v_add_f32_e32 v0, v0, v104
	v_xor_b32_e32 v104, 2, v101
	v_cmp_lt_i32_e64 s[0:1], v104, v103
	v_cndmask_b32_e64 v107, v97, 0, vcc
	v_cndmask_b32_e64 v97, 23, 19, vcc
	v_cndmask_b32_e64 v104, v101, v104, s[0:1]
	v_lshlrev_b32_e32 v104, 2, v104
	ds_bpermute_b32 v108, v104, v0
	v_mov_b32_e32 v104, s21
	v_cndmask_b32_e32 v104, v106, v104, vcc
	v_cndmask_b32_e32 v106, v98, v95, vcc
	v_xor_b32_e32 v95, 4, v101
	v_cmp_lt_i32_e64 s[0:1], v95, v103
	s_waitcnt lgkmcnt(0)
	v_add_f32_e32 v0, v0, v108
	v_ashrrev_i32_e32 v3, 31, v2
	v_cndmask_b32_e64 v95, v101, v95, s[0:1]
	v_lshlrev_b32_e32 v95, 2, v95
	ds_bpermute_b32 v95, v95, v0
	v_lshlrev_b64 v[2:3], v97, v[2:3]
	v_lshl_add_u64 v[2:3], v[104:105], 0, v[2:3]
	v_lshlrev_b64 v[104:105], 11, v[106:107]
	v_lshl_add_u64 v[2:3], v[2:3], 0, v[104:105]
	s_waitcnt lgkmcnt(0)
	v_add_f32_e32 v95, v0, v95
	v_xor_b32_e32 v0, 8, v101
	v_cmp_lt_i32_e32 vcc, v0, v103
	v_cvt_pk_bf16_f32 v104, v80, v81
	v_cvt_pk_bf16_f32 v105, v82, v83
	v_mov_b32_e32 v98, v102
	s_nop 0
	v_cndmask_b32_e32 v0, v101, v0, vcc
	v_lshlrev_b32_e32 v0, 2, v0
	ds_bpermute_b32 v97, v0, v95
	v_lshlrev_b32_e32 v0, 1, v88
	v_lshl_add_u64 v[2:3], v[2:3], 0, v[0:1]
	global_store_dwordx2 v[2:3], v[104:105], off
	v_cvt_pk_bf16_f32 v104, v60, v61
	s_waitcnt lgkmcnt(0)
	v_add_f32_e32 v0, v95, v97
	v_xor_b32_e32 v95, 16, v101
	v_cmp_lt_i32_e32 vcc, v95, v103
	v_cvt_pk_bf16_f32 v105, v62, v63
	global_store_dwordx2 v[2:3], v[104:105], off offset:512
	v_cvt_pk_bf16_f32 v104, v32, v33
	v_cvt_pk_bf16_f32 v105, v34, v35
	global_store_dwordx2 v[2:3], v[104:105], off offset:1024
	v_cndmask_b32_e32 v95, v101, v95, vcc
	v_lshlrev_b32_e32 v95, 2, v95
	ds_bpermute_b32 v95, v95, v0
	v_cvt_pk_bf16_f32 v104, v20, v21
	v_cvt_pk_bf16_f32 v105, v22, v23
	global_store_dwordx2 v[2:3], v[104:105], off offset:1536
	v_pk_add_f32 v[104:105], v[28:29], 1.0 op_sel_hi:[1,0]
	s_waitcnt lgkmcnt(0)
	v_add_f32_e32 v0, v0, v95
	v_xor_b32_e32 v95, 32, v101
	v_cmp_lt_i32_e32 vcc, v95, v103
	s_nop 1
	v_cndmask_b32_e32 v95, v101, v95, vcc
	v_lshlrev_b32_e32 v95, 2, v95
	ds_bpermute_b32 v95, v95, v0
	s_waitcnt lgkmcnt(0)
	v_add_f32_e32 v0, v0, v95
	v_fmamk_f32 v0, v0, 0x3a800000, v99
	v_mul_f32_e32 v95, 0x4b800000, v0
	v_cmp_gt_f32_e32 vcc, s24, v0
	s_nop 1
	v_cndmask_b32_e32 v0, v0, v95, vcc
	v_rsq_f32_e32 v0, v0
	s_nop 0
	v_mul_f32_e32 v2, 0x45800000, v0
	v_cndmask_b32_e32 v0, v0, v2, vcc
	v_pk_mul_f32 v[80:81], v[80:81], v[0:1] op_sel_hi:[1,0]
	v_pk_mul_f32 v[2:3], v[82:83], v[0:1] op_sel_hi:[1,0]
	v_pk_mul_f32 v[80:81], v[4:5], v[80:81]
	v_pk_mul_f32 v[2:3], v[6:7], v[2:3]
	v_pk_add_f32 v[82:83], v[30:31], 1.0 op_sel_hi:[1,0]
	v_pk_fma_f32 v[80:81], v[104:105], v[80:81], v[24:25]
	v_pk_fma_f32 v[2:3], v[82:83], v[2:3], v[26:27]
	v_cvt_pk_bf16_f32 v80, v80, v81
	v_pk_mul_f32 v[60:61], v[60:61], v[0:1] op_sel_hi:[1,0]
	v_cvt_pk_bf16_f32 v81, v2, v3
	global_store_dwordx2 v[90:91], v[80:81], off
	v_pk_mul_f32 v[2:3], v[62:63], v[0:1] op_sel_hi:[1,0]
	v_pk_mul_f32 v[60:61], v[8:9], v[60:61]
	v_pk_add_f32 v[80:81], v[48:49], 1.0 op_sel_hi:[1,0]
	v_pk_mul_f32 v[2:3], v[10:11], v[2:3]
	v_pk_add_f32 v[62:63], v[50:51], 1.0 op_sel_hi:[1,0]
	v_pk_fma_f32 v[60:61], v[80:81], v[60:61], v[40:41]
	v_pk_fma_f32 v[2:3], v[62:63], v[2:3], v[42:43]
	v_cvt_pk_bf16_f32 v60, v60, v61
	v_pk_mul_f32 v[32:33], v[32:33], v[0:1] op_sel_hi:[1,0]
	v_cvt_pk_bf16_f32 v61, v2, v3
	global_store_dwordx2 v[90:91], v[60:61], off offset:512
	v_pk_mul_f32 v[2:3], v[34:35], v[0:1] op_sel_hi:[1,0]
	v_pk_mul_f32 v[32:33], v[12:13], v[32:33]
	v_pk_add_f32 v[60:61], v[56:57], 1.0 op_sel_hi:[1,0]
	v_pk_mul_f32 v[2:3], v[14:15], v[2:3]
	v_pk_add_f32 v[34:35], v[58:59], 1.0 op_sel_hi:[1,0]
	v_pk_fma_f32 v[32:33], v[60:61], v[32:33], v[36:37]
	v_pk_fma_f32 v[2:3], v[34:35], v[2:3], v[38:39]
	v_cvt_pk_bf16_f32 v32, v32, v33
	v_pk_mul_f32 v[20:21], v[20:21], v[0:1] op_sel_hi:[1,0]
	v_cvt_pk_bf16_f32 v33, v2, v3
	global_store_dwordx2 v[90:91], v[32:33], off offset:1024
	v_pk_mul_f32 v[2:3], v[22:23], v[0:1] op_sel_hi:[1,0]
	v_pk_mul_f32 v[20:21], v[16:17], v[20:21]
	v_pk_add_f32 v[32:33], v[52:53], 1.0 op_sel_hi:[1,0]
	v_pk_mul_f32 v[2:3], v[18:19], v[2:3]
	v_pk_add_f32 v[22:23], v[54:55], 1.0 op_sel_hi:[1,0]
	v_pk_fma_f32 v[20:21], v[32:33], v[20:21], v[44:45]
	v_pk_fma_f32 v[2:3], v[22:23], v[2:3], v[46:47]
	v_cvt_pk_bf16_f32 v20, v20, v21
	s_waitcnt vmcnt(3)
	v_mov_b64_e32 v[32:33], v[68:69]
	v_cvt_pk_bf16_f32 v21, v2, v3
	global_store_dwordx2 v[90:91], v[20:21], off offset:1536
	v_mov_b64_e32 v[20:21], v[64:65]
	v_mov_b64_e32 v[60:61], v[72:73]
	v_mov_b64_e32 v[82:83], v[78:79]
	v_lshl_add_u64 v[90:91], v[90:91], 0, s[14:15]
	v_mov_b64_e32 v[22:23], v[66:67]
	v_mov_b64_e32 v[34:35], v[70:71]
	v_mov_b64_e32 v[62:63], v[74:75]
	v_mov_b64_e32 v[80:81], v[76:77]
	s_andn2_b64 exec, exec, s[12:13]
	s_cbranch_execz .LBB0_117
; DI void rowpass(const Cx& a, int mode, int l, int tid, int gw, int NGW) {
;     ...
;     for (int row = r0; row < r1; ++row) {
;         if (row + 1 < r1) RP_LOAD(row + 1, xfn, xbn, yn, sn_);
;         const int b = row / NB, n = row - b * NB; const bool lat = n < SEQ; const int mv = lat ? b : 16;
;         if (!(skipc && !lat)) {
;             if (mv != cur_mv) { cur_mv = mv;
;                 const float* mb = MOD + ((size_t)l * NMOD + mv) * MODW; const float* mb2 = MOD + ((size_t)l2 * NMOD + mv) * MODW;
; #pragma unroll
;                 for (int j = 0; j < 4; ++j) { const int c = 4 * lane + 256 * j;
;                     if (mode != 0) gtv[j] = *(const f32x4*)(mb + (mode == 1 ? 2 * DM : 5 * DM) + c);
;                     if (!last) { shv[j] = *(const f32x4*)(mb2 + (mode == 1 ? 3 * DM : 0) + c); scv[j] = *(const f32x4*)(mb2 + (mode == 1 ? 4 * DM : DM) + c); } } }
.LBB0_113:
	v_add_u32_e32 v102, 1, v98
	v_cmp_lt_i32_e32 vcc, v102, v100
	v_cmp_ge_i32_e64 s[2:3], v102, v100
	v_lshlrev_b32_e32 v0, 2, v88
	s_and_saveexec_b64 s[0:1], vcc
	s_cbranch_execz .LBB0_115
	v_mul_hi_i32 v2, v102, s18
	v_lshrrev_b32_e32 v3, 31, v2
	v_ashrrev_i32_e32 v2, 11, v2
	v_add_u32_e32 v2, v2, v3
	v_mad_i32_i24 v64, v2, s19, v98
	v_add_u32_e32 v66, 1, v64
	v_cmp_gt_i32_e32 vcc, s20, v66
	v_ashrrev_i32_e32 v3, 31, v2
	v_add_u32_e32 v64, 0xfffff001, v64
	v_ashrrev_i32_e32 v65, 31, v66
	v_cndmask_b32_e64 v68, 20, 24, vcc
	v_cndmask_b32_e32 v65, 0, v65, vcc
	v_cndmask_b32_e32 v64, v64, v66, vcc
	v_cndmask_b32_e32 v67, v87, v85, vcc
	v_cndmask_b32_e32 v66, v86, v84, vcc
	v_lshlrev_b64 v[2:3], v68, v[2:3]
	v_lshl_add_u64 v[2:3], v[66:67], 0, v[2:3]
	v_lshlrev_b64 v[64:65], 12, v[64:65]
	v_lshl_add_u64 v[2:3], v[2:3], 0, v[64:65]
	v_lshl_add_u64 v[2:3], v[2:3], 0, v[0:1]
	global_load_dwordx4 v[76:79], v[2:3], off
	global_load_dwordx4 v[72:75], v[2:3], off offset:1024
	global_load_dwordx4 v[68:71], v[2:3], off offset:2048
	global_load_dwordx4 v[64:67], v[2:3], off offset:3072
.LBB0_115:
	s_or_b64 exec, exec, s[0:1]
	v_mul_hi_i32 v2, v98, s18
	v_lshrrev_b32_e32 v3, 31, v2
	v_ashrrev_i32_e32 v2, 11, v2
	v_add_u32_e32 v2, v2, v3
	v_mad_i32_i24 v98, v2, s19, v98
	v_cmp_lt_i32_e32 vcc, s23, v98
	s_nop 1
	v_cndmask_b32_e64 v3, v2, 16, vcc
	v_cmp_ne_u32_e64 s[0:1], v3, v93
	s_and_saveexec_b64 s[16:17], s[0:1]
	s_cbranch_execz .LBB0_112
	v_mul_hi_i32_i24_e32 v25, 0x6000, v3
	v_mul_i32_i24_e32 v24, 0x6000, v3
	v_lshl_add_u64 v[24:25], s[10:11], 0, v[24:25]
	v_lshl_add_u64 v[44:45], v[24:25], 0, s[8:9]
	v_mov_b32_e32 v93, v1
	v_lshl_add_u64 v[36:37], v[44:45], 0, v[0:1]
	v_lshl_add_u64 v[104:105], v[24:25], 0, v[0:1]
	v_lshl_add_u64 v[106:107], v[44:45], 0, v[92:93]
	v_mov_b32_e32 v95, v1
	v_mov_b32_e32 v97, v1
	global_load_dwordx4 v[24:27], v[104:105], off
	global_load_dwordx4 v[28:31], v[36:37], off
	v_lshl_add_u64 v[108:109], v[44:45], 0, v[94:95]
	global_load_dwordx4 v[40:43], v[104:105], off offset:1024
	global_load_dwordx4 v[36:39], v[104:105], off offset:2048
	v_lshl_add_u64 v[110:111], v[44:45], 0, v[96:97]
	global_load_dwordx4 v[48:51], v[106:107], off
	global_load_dwordx4 v[44:47], v[104:105], off offset:3072
	global_load_dwordx4 v[56:59], v[108:109], off
	global_load_dwordx4 v[52:55], v[110:111], off
	v_mov_b32_e32 v93, v3
	s_waitcnt vmcnt(0) lgkmcnt(0)
	s_branch .LBB0_112
